# baseline (speedup 1.0000x reference)
; __device__ __forceinline__ void phase_fox_attn(const Params& p, char* smem) {
;     ...
; #pragma unroll
;       for (int qb = 0; qb < 2; ++qb) {
;         const float mu = (m[qb] == -INFINITY) ? 0.f : m[qb];
;         float ps = 0.f;
; #pragma unroll
;         for (int kb = 0; kb < 4; ++kb)
; #pragma unroll
;           for (int r = 0; r < 4; ++r) {
;             float pv = __builtin_amdgcn_exp2f(s[kb][qb][r] - mu);
;             s[kb][qb][r] = pv;
;             ps += pv;
;           }
;         l[qb] += ps;
;       }
;       __builtin_amdgcn_s_setprio(1);
; #pragma unroll
;       for (int kp = 0; kp < 2; ++kp) {
;         bf16x8 pf[2];
; #pragma unroll
;         for (int qb = 0; qb < 2; ++qb) {
;           u32x4 u;
;           u.x = pack2(s[2 * kp][qb][0], s[2 * kp][qb][1]); u.y = pack2(s[2 * kp][qb][2], s[2 * kp][qb][3]);
;           u.z = pack2(s[2 * kp + 1][qb][0], s[2 * kp + 1][qb][1]); u.w = pack2(s[2 * kp + 1][qb][2], s[2 * kp + 1][qb][3]);
;           pf[qb] = *(bf16x8*)&u;
;         }
;         const int vo0 = vb_ ^ ((kp * 4) << 4), vo1 = vb_ ^ ((kp * 4 + 2) << 4);
; #pragma unroll
;         for (int db = 0; db < 8; ++db) {
;           u32x2 v0 = *(const u32x2*)(sV + db * 2048 + vo0);
;           u32x2 v1 = *(const u32x2*)(sV + db * 2048 + vo1);
;           u32x4 u; u.x = v0.x; u.y = v0.y; u.z = v1.x; u.w = v1.y;
;           bf16x8 a = *(bf16x8*)&u;
;           o[db][0] = __builtin_amdgcn_mfma_f32_16x16x32_bf16(a, pf[0], o[db][0], 0, 0, 0);
;           o[db][1] = __builtin_amdgcn_mfma_f32_16x16x32_bf16(a, pf[1], o[db][1], 0, 0, 0);
;         }
.LBB0_200:
	v_cmp_neq_f32_e32 vcc, s0, v138
	s_nop 1
	v_cndmask_b32_e32 v168, 0, v138, vcc
	v_sub_f32_e32 v139, v139, v168
	v_exp_f32_e32 v169, v139
	v_sub_f32_e32 v139, v143, v168
	v_exp_f32_e32 v171, v139
	v_sub_f32_e32 v139, v145, v168
	v_exp_f32_e32 v173, v139
	v_sub_f32_e32 v139, v146, v168
	v_exp_f32_e32 v175, v139
	v_sub_f32_e32 v139, v147, v168
	v_exp_f32_e32 v177, v139
	v_sub_f32_e32 v139, v148, v168
	v_exp_f32_e32 v179, v139
	v_sub_f32_e32 v139, v149, v168
	v_exp_f32_e32 v181, v139
	v_sub_f32_e32 v139, v150, v168
	v_exp_f32_e32 v183, v139
	v_sub_f32_e32 v139, v151, v168
	v_exp_f32_e32 v185, v139
	v_sub_f32_e32 v139, v152, v168
	v_exp_f32_e32 v187, v139
	v_sub_f32_e32 v139, v153, v168
	v_exp_f32_e32 v189, v139
	v_sub_f32_e32 v139, v154, v168
	v_exp_f32_e32 v191, v139
	v_sub_f32_e32 v139, v155, v168
	v_exp_f32_e32 v155, v139
	v_sub_f32_e32 v139, v157, v168
	v_exp_f32_e32 v193, v139
	v_sub_f32_e32 v139, v158, v168
	v_exp_f32_e32 v195, v139
	v_sub_f32_e32 v139, v159, v168
	v_cmp_neq_f32_e32 vcc, s0, v137
	v_exp_f32_e32 v197, v139
	s_nop 0
	v_cndmask_b32_e32 v139, 0, v137, vcc
	v_sub_f32_e32 v143, v160, v139
	v_exp_f32_e32 v168, v143
	v_sub_f32_e32 v143, v161, v139
	v_exp_f32_e32 v170, v143
	v_sub_f32_e32 v143, v164, v139
	v_exp_f32_e32 v172, v143
	v_sub_f32_e32 v143, v165, v139
	v_exp_f32_e32 v174, v143
	v_sub_f32_e32 v143, v166, v139
	v_exp_f32_e32 v176, v143
	v_sub_f32_e32 v143, v167, v139
	v_pk_add_f32 v[146:147], v[168:169], 0 op_sel_hi:[1,0]
	v_exp_f32_e32 v178, v143
	v_pk_add_f32 v[146:147], v[170:171], v[146:147]
	v_sub_f32_e32 v143, v162, v139
	v_pk_add_f32 v[146:147], v[172:173], v[146:147]
	v_exp_f32_e32 v180, v143
	v_sub_f32_e32 v143, v163, v139
	v_sub_f32_e32 v96, v96, v139
	v_pk_add_f32 v[146:147], v[174:175], v[146:147]
	v_exp_f32_e32 v182, v143
	v_sub_f32_e32 v100, v100, v139
	v_exp_f32_e32 v154, v96
	v_sub_f32_e32 v96, v97, v139
	v_pk_add_f32 v[146:147], v[176:177], v[146:147]
	v_exp_f32_e32 v184, v100
	v_sub_f32_e32 v100, v101, v139
	v_exp_f32_e32 v192, v96
	v_sub_f32_e32 v96, v98, v139
	v_pk_add_f32 v[146:147], v[178:179], v[146:147]
	v_exp_f32_e32 v186, v100
	v_sub_f32_e32 v100, v102, v139
	v_exp_f32_e32 v194, v96
	v_sub_f32_e32 v96, v99, v139
	v_exp_f32_e32 v188, v100
	v_sub_f32_e32 v100, v103, v139
	v_exp_f32_e32 v196, v96
	v_pk_add_f32 v[96:97], v[180:181], v[146:147]
	v_exp_f32_e32 v190, v100
	v_pk_add_f32 v[96:97], v[182:183], v[96:97]
	v_add_u32_e32 v139, s6, v104
	v_pk_add_f32 v[96:97], v[184:185], v[96:97]
	v_xad_u32 v143, v104, 32, s6
	v_pk_add_f32 v[96:97], v[186:187], v[96:97]
	ds_read_b64 v[150:151], v139 offset:32768
	ds_read_b64 v[152:153], v143 offset:32768
	v_pk_add_f32 v[96:97], v[188:189], v[96:97]
	ds_read_b64 v[100:101], v139 offset:34816
	ds_read_b64 v[102:103], v143 offset:34816
	v_pk_add_f32 v[96:97], v[190:191], v[96:97]
	v_cvt_pk_bf16_f32 v146, v169, v171
	v_pk_add_f32 v[96:97], v[154:155], v[96:97]
	v_cvt_pk_bf16_f32 v147, v173, v175
	v_pk_add_f32 v[96:97], v[192:193], v[96:97]
	v_cvt_pk_bf16_f32 v148, v177, v179
	v_pk_add_f32 v[96:97], v[194:195], v[96:97]
	v_cvt_pk_bf16_f32 v149, v181, v183
	v_pk_add_f32 v[96:97], v[196:197], v[96:97]
	v_cvt_pk_bf16_f32 v158, v168, v170
	v_pk_add_f32 v[108:109], v[108:109], v[96:97]
	v_cvt_pk_bf16_f32 v159, v172, v174
	v_cvt_pk_bf16_f32 v160, v176, v178
	v_cvt_pk_bf16_f32 v161, v180, v182
	s_setprio 1
	s_waitcnt lgkmcnt(2)
	v_mfma_f32_16x16x32_bf16 v[48:51], v[150:153], v[146:149], v[48:51]
	v_mfma_f32_16x16x32_bf16 v[28:31], v[150:153], v[158:161], v[28:31]
	ds_read_b64 v[96:97], v139 offset:36864
	ds_read_b64 v[98:99], v143 offset:36864
	ds_read_b64 v[150:151], v139 offset:38912
	ds_read_b64 v[152:153], v143 offset:38912
	s_waitcnt lgkmcnt(4)
	v_mfma_f32_16x16x32_bf16 v[52:55], v[100:103], v[146:149], v[52:55]
	v_mfma_f32_16x16x32_bf16 v[24:27], v[100:103], v[158:161], v[24:27]
	s_waitcnt lgkmcnt(2)
; __device__ __forceinline__ void phase_fox_attn(const Params& p, char* smem) {
;     ...
;       for (int kp = 0; kp < 2; ++kp) {
;         bf16x8 pf[2];
; #pragma unroll
;         for (int qb = 0; qb < 2; ++qb) {
;           u32x4 u;
;           u.x = pack2(s[2 * kp][qb][0], s[2 * kp][qb][1]); u.y = pack2(s[2 * kp][qb][2], s[2 * kp][qb][3]);
;           u.z = pack2(s[2 * kp + 1][qb][0], s[2 * kp + 1][qb][1]); u.w = pack2(s[2 * kp + 1][qb][2], s[2 * kp + 1][qb][3]);
;           pf[qb] = *(bf16x8*)&u;
;         }
;         const int vo0 = vb_ ^ ((kp * 4) << 4), vo1 = vb_ ^ ((kp * 4 + 2) << 4);
; #pragma unroll
;         for (int db = 0; db < 8; ++db) {
;           u32x2 v0 = *(const u32x2*)(sV + db * 2048 + vo0);
;           u32x2 v1 = *(const u32x2*)(sV + db * 2048 + vo1);
;           u32x4 u; u.x = v0.x; u.y = v0.y; u.z = v1.x; u.w = v1.y;
;           bf16x8 a = *(bf16x8*)&u;
;           o[db][0] = __builtin_amdgcn_mfma_f32_16x16x32_bf16(a, pf[0], o[db][0], 0, 0, 0);
;           o[db][1] = __builtin_amdgcn_mfma_f32_16x16x32_bf16(a, pf[1], o[db][1], 0, 0, 0);
;         }
;       }
;       __builtin_amdgcn_s_setprio(0);
;     }
	v_mfma_f32_16x16x32_bf16 v[56:59], v[96:99], v[146:149], v[56:59]
	v_mfma_f32_16x16x32_bf16 v[20:23], v[96:99], v[158:161], v[20:23]
	ds_read_b64 v[100:101], v139 offset:40960
	ds_read_b64 v[102:103], v143 offset:40960
	ds_read_b64 v[96:97], v139 offset:43008
	ds_read_b64 v[98:99], v143 offset:43008
	s_waitcnt lgkmcnt(4)
	v_mfma_f32_16x16x32_bf16 v[60:63], v[150:153], v[146:149], v[60:63]
	v_mfma_f32_16x16x32_bf16 v[16:19], v[150:153], v[158:161], v[16:19]
	s_waitcnt lgkmcnt(2)
	v_mfma_f32_16x16x32_bf16 v[44:47], v[100:103], v[146:149], v[44:47]
	v_mfma_f32_16x16x32_bf16 v[12:15], v[100:103], v[158:161], v[12:15]
	ds_read_b64 v[150:151], v139 offset:45056
	ds_read_b64 v[152:153], v143 offset:45056
	ds_read_b64 v[100:101], v139 offset:47104
	ds_read_b64 v[102:103], v143 offset:47104
	s_waitcnt lgkmcnt(4)
	v_mfma_f32_16x16x32_bf16 v[40:43], v[96:99], v[146:149], v[40:43]
	v_mfma_f32_16x16x32_bf16 v[8:11], v[96:99], v[158:161], v[8:11]
	s_waitcnt lgkmcnt(2)
	v_mfma_f32_16x16x32_bf16 v[36:39], v[150:153], v[146:149], v[36:39]
	v_mfma_f32_16x16x32_bf16 v[4:7], v[150:153], v[158:161], v[4:7]
	v_xor_b32_e32 v143, 0x60, v104
	v_xad_u32 v104, v104, 64, s6
	v_add_u32_e32 v139, s6, v143
	ds_read_b64 v[96:97], v104 offset:32768
	ds_read_b64 v[98:99], v139 offset:32768
	ds_read_b64 v[150:151], v104 offset:34816
	ds_read_b64 v[152:153], v139 offset:34816
	s_waitcnt lgkmcnt(4)
	v_mfma_f32_16x16x32_bf16 v[32:35], v[100:103], v[146:149], v[32:35]
	v_cvt_pk_bf16_f32 v146, v185, v187
	v_cvt_pk_bf16_f32 v147, v189, v191
	v_cvt_pk_bf16_f32 v148, v155, v193
	v_cvt_pk_bf16_f32 v149, v195, v197
	v_mfma_f32_16x16x32_bf16 v[0:3], v[100:103], v[158:161], v[0:3]
	v_cvt_pk_bf16_f32 v158, v184, v186
	v_cvt_pk_bf16_f32 v159, v188, v190
	v_cvt_pk_bf16_f32 v160, v154, v192
	v_cvt_pk_bf16_f32 v161, v194, v196
	s_waitcnt lgkmcnt(2)
	v_mfma_f32_16x16x32_bf16 v[48:51], v[96:99], v[146:149], v[48:51]
	v_mfma_f32_16x16x32_bf16 v[28:31], v[96:99], v[158:161], v[28:31]
	ds_read_b64 v[100:101], v104 offset:36864
	ds_read_b64 v[102:103], v139 offset:36864
	ds_read_b64 v[96:97], v104 offset:38912
	ds_read_b64 v[98:99], v139 offset:38912
	s_waitcnt lgkmcnt(4)
	v_mfma_f32_16x16x32_bf16 v[52:55], v[150:153], v[146:149], v[52:55]
	v_mfma_f32_16x16x32_bf16 v[24:27], v[150:153], v[158:161], v[24:27]
	s_waitcnt lgkmcnt(2)
	v_mfma_f32_16x16x32_bf16 v[56:59], v[100:103], v[146:149], v[56:59]
	v_mfma_f32_16x16x32_bf16 v[20:23], v[100:103], v[158:161], v[20:23]
	ds_read_b64 v[150:151], v104 offset:40960
	ds_read_b64 v[152:153], v139 offset:40960
	ds_read_b64 v[100:101], v104 offset:43008
	ds_read_b64 v[102:103], v139 offset:43008
	s_waitcnt lgkmcnt(4)
	v_mfma_f32_16x16x32_bf16 v[60:63], v[96:99], v[146:149], v[60:63]
	v_mfma_f32_16x16x32_bf16 v[16:19], v[96:99], v[158:161], v[16:19]
	s_waitcnt lgkmcnt(2)
	v_mfma_f32_16x16x32_bf16 v[44:47], v[150:153], v[146:149], v[44:47]
	v_mfma_f32_16x16x32_bf16 v[12:15], v[150:153], v[158:161], v[12:15]
	ds_read_b64 v[96:97], v104 offset:45056
	ds_read_b64 v[98:99], v139 offset:45056
	ds_read_b64 v[150:151], v104 offset:47104
	ds_read_b64 v[152:153], v139 offset:47104
	s_waitcnt lgkmcnt(4)
	v_mfma_f32_16x16x32_bf16 v[40:43], v[100:103], v[146:149], v[40:43]
	v_mfma_f32_16x16x32_bf16 v[8:11], v[100:103], v[158:161], v[8:11]
	s_waitcnt lgkmcnt(2)
	v_mfma_f32_16x16x32_bf16 v[36:39], v[96:99], v[146:149], v[36:39]
	v_mfma_f32_16x16x32_bf16 v[4:7], v[96:99], v[158:161], v[4:7]
	s_waitcnt lgkmcnt(0)
	v_mfma_f32_16x16x32_bf16 v[32:35], v[150:153], v[146:149], v[32:35]
	v_mfma_f32_16x16x32_bf16 v[0:3], v[150:153], v[158:161], v[0:3]
	s_setprio 0
	s_add_i32 s85, s85, 1
	s_add_i32 s84, s84, -1
	s_sub_i32 s86, s86, 64
	s_cmp_eq_u32 s35, s85
	s_cbranch_scc1 .LBB0_194

; __device__ __forceinline__ void phase_fox_attn(const Params& p, char* smem) {
;     ...
; #pragma unroll
;       for (int qb = 0; qb < 2; ++qb) {
;         const int qpos = q0 + wave * 32 + qb * 16 + lr;
;         float mx = -INFINITY;
; #pragma unroll
;         for (int kb = 0; kb < 4; ++kb)
; #pragma unroll
;           for (int r = 0; r < 4; ++r) {
;             int kl = kb * 16 + g * 4 + r;
;             float v = s[kb][qb][r] + (ct[qb] - sCt[kl]);
;             if (diag && (kv0 + kl > qpos)) v = -INFINITY;
;             s[kb][qb][r] = v;
;             mx = fmaxf(mx, v);
;           }
;         mx = fmaxf(mx, __shfl_xor(mx, 16));
;         mx = fmaxf(mx, __shfl_xor(mx, 32));
;         mx2[qb] = mx;
;       }
;       if (__any((mx2[0] > m[0] + 8.f) || (mx2[1] > m[1] + 8.f))) {
; #pragma unroll
;         for (int qb = 0; qb < 2; ++qb) {
;           const float mnew = fmaxf(m[qb], mx2[qb]);
;           const float alpha = (mnew == -INFINITY) ? 1.f : __builtin_amdgcn_exp2f(m[qb] - mnew);
;           m[qb] = mnew;
;           l[qb] *= alpha;
; #pragma unroll
;           for (int db = 0; db < 8; ++db) { o[db][qb][0] *= alpha; o[db][qb][1] *= alpha; o[db][qb][2] *= alpha; o[db][qb][3] *= alpha; }
;         }
;       }
.Lfox_join:
	v_max3_f32 v168, v170, v98, v99
	ds_bpermute_b32 v209, v194, v208
	ds_bpermute_b32 v169, v194, v168
	v_lshlrev_b32_e32 v170, 2, v195
	s_waitcnt lgkmcnt(0)
	v_max_f32_e32 v171, v208, v209
	v_max_f32_e32 v168, v168, v169
	ds_bpermute_b32 v172, v170, v171
	ds_bpermute_b32 v170, v170, v168
	s_waitcnt lgkmcnt(0)
	v_max_f32_e32 v169, v171, v172
	v_max_f32_e32 v168, v168, v170
	v_add_f32_e32 v170, 0x41000000, v138
	v_cmp_gt_f32_e32 vcc, v169, v170
	v_add_f32_e32 v170, 0x41000000, v137
	v_cmp_gt_f32_e64 s[4:5], v168, v170
	s_or_b64 vcc, vcc, s[4:5]
	s_cbranch_vccz .LBB0_200
	v_max_f32_e32 v169, v169, v169
	v_max_f32_e32 v170, v138, v138
	v_max_f32_e32 v170, v170, v169
	v_max_f32_e32 v168, v168, v168
	v_max_f32_e32 v169, v137, v137
	v_sub_f32_e32 v138, v138, v170
	v_max_f32_e32 v171, v169, v168
	v_exp_f32_e32 v138, v138
	v_sub_f32_e32 v137, v137, v171
	v_exp_f32_e32 v137, v137
	v_cmp_neq_f32_e32 vcc, s0, v170
	s_nop 1
	v_cndmask_b32_e32 v169, 1.0, v138, vcc
	v_cmp_neq_f32_e32 vcc, s0, v171
	v_mov_b32_e32 v138, v169
	v_pk_mul_f32 v[50:51], v[50:51], v[138:139] op_sel_hi:[1,0]
	v_cndmask_b32_e32 v168, 1.0, v137, vcc
	v_pk_mul_f32 v[48:49], v[48:49], v[138:139] op_sel_hi:[1,0]
	v_pk_mul_f32 v[54:55], v[54:55], v[138:139] op_sel_hi:[1,0]
	v_pk_mul_f32 v[52:53], v[52:53], v[138:139] op_sel_hi:[1,0]
	v_pk_mul_f32 v[58:59], v[58:59], v[138:139] op_sel_hi:[1,0]
	v_pk_mul_f32 v[56:57], v[56:57], v[138:139] op_sel_hi:[1,0]
	v_pk_mul_f32 v[62:63], v[62:63], v[138:139] op_sel_hi:[1,0]
	v_pk_mul_f32 v[60:61], v[60:61], v[138:139] op_sel_hi:[1,0]
	v_pk_mul_f32 v[46:47], v[46:47], v[138:139] op_sel_hi:[1,0]
	v_pk_mul_f32 v[44:45], v[44:45], v[138:139] op_sel_hi:[1,0]
	v_pk_mul_f32 v[42:43], v[42:43], v[138:139] op_sel_hi:[1,0]
	v_pk_mul_f32 v[40:41], v[40:41], v[138:139] op_sel_hi:[1,0]
	v_pk_mul_f32 v[38:39], v[38:39], v[138:139] op_sel_hi:[1,0]
	v_pk_mul_f32 v[36:37], v[36:37], v[138:139] op_sel_hi:[1,0]
	v_pk_mul_f32 v[34:35], v[34:35], v[138:139] op_sel_hi:[1,0]
	v_pk_mul_f32 v[32:33], v[32:33], v[138:139] op_sel_hi:[1,0]
	v_pk_mul_f32 v[108:109], v[108:109], v[168:169]
	v_pk_mul_f32 v[30:31], v[30:31], v[168:169] op_sel_hi:[1,0]
	v_pk_mul_f32 v[28:29], v[28:29], v[168:169] op_sel_hi:[1,0]
	v_pk_mul_f32 v[26:27], v[26:27], v[168:169] op_sel_hi:[1,0]
	v_pk_mul_f32 v[24:25], v[24:25], v[168:169] op_sel_hi:[1,0]
	v_pk_mul_f32 v[22:23], v[22:23], v[168:169] op_sel_hi:[1,0]
	v_pk_mul_f32 v[20:21], v[20:21], v[168:169] op_sel_hi:[1,0]
	v_pk_mul_f32 v[18:19], v[18:19], v[168:169] op_sel_hi:[1,0]
	v_pk_mul_f32 v[16:17], v[16:17], v[168:169] op_sel_hi:[1,0]
	v_pk_mul_f32 v[14:15], v[14:15], v[168:169] op_sel_hi:[1,0]
	v_pk_mul_f32 v[12:13], v[12:13], v[168:169] op_sel_hi:[1,0]
	v_pk_mul_f32 v[10:11], v[10:11], v[168:169] op_sel_hi:[1,0]
	v_pk_mul_f32 v[8:9], v[8:9], v[168:169] op_sel_hi:[1,0]
	v_pk_mul_f32 v[6:7], v[6:7], v[168:169] op_sel_hi:[1,0]
	v_pk_mul_f32 v[4:5], v[4:5], v[168:169] op_sel_hi:[1,0]
	v_pk_mul_f32 v[2:3], v[2:3], v[168:169] op_sel_hi:[1,0]
	v_pk_mul_f32 v[0:1], v[0:1], v[168:169] op_sel_hi:[1,0]
	v_mov_b32_e32 v137, v171
	v_mov_b32_e32 v138, v170
	s_branch .LBB0_200
.Lfox_fast:
	v_cndmask_b32_e32 v195, v126, v129, vcc
	s_waitcnt lgkmcnt(0)
	v_sub_f32_e32 v139, v130, v186
	v_add_f32_e32 v139, v178, v139
	v_sub_f32_e32 v143, v130, v187
	v_add_f32_e32 v143, v179, v143
	v_sub_f32_e32 v145, v130, v188
	v_add_f32_e32 v145, v180, v145
	v_sub_f32_e32 v146, v130, v189
	v_add_f32_e32 v146, v181, v146
	v_max3_f32 v147, v139, s0, v143
	v_max3_f32 v149, v147, v145, v146
	v_sub_f32_e32 v147, v130, v190
	v_add_f32_e32 v147, v182, v147
	v_sub_f32_e32 v148, v130, v191
	v_add_f32_e32 v148, v183, v148
	ds_read_b128 v[178:181], v151 offset:128
	v_max3_f32 v152, v149, v147, v148
	v_sub_f32_e32 v149, v130, v192
	v_add_f32_e32 v149, v184, v149
	v_sub_f32_e32 v150, v130, v193
	v_add_f32_e32 v150, v185, v150
	ds_read_b128 v[182:185], v151 offset:192
	s_waitcnt lgkmcnt(0)
	v_sub_f32_e32 v151, v130, v178
	v_add_f32_e32 v151, v162, v151
	v_max3_f32 v153, v152, v149, v150
	v_sub_f32_e32 v152, v130, v179
	v_add_f32_e32 v152, v163, v152
	v_max3_f32 v155, v153, v151, v152
	v_sub_f32_e32 v153, v130, v180
	v_add_f32_e32 v153, v164, v153
	v_sub_f32_e32 v154, v130, v181
	v_add_f32_e32 v154, v165, v154
	v_max3_f32 v158, v155, v153, v154
	v_sub_f32_e32 v155, v130, v182
	v_add_f32_e32 v155, v166, v155
	v_sub_f32_e32 v157, v130, v183
	v_add_f32_e32 v157, v167, v157
	v_max3_f32 v162, v158, v155, v157
	v_sub_f32_e32 v158, v130, v184
	v_add_f32_e32 v158, v168, v158
	v_sub_f32_e32 v163, v130, v185
	v_add_f32_e32 v159, v169, v163
	v_max3_f32 v208, v162, v158, v159
	v_sub_f32_e32 v162, v131, v186
	v_add_f32_e32 v160, v170, v162
	v_sub_f32_e32 v162, v131, v187
	v_add_f32_e32 v161, v171, v162
	v_sub_f32_e32 v163, v131, v188
	v_add_f32_e32 v164, v172, v163
	v_sub_f32_e32 v163, v131, v189
	v_add_f32_e32 v165, v173, v163
	v_sub_f32_e32 v163, v131, v190
	v_add_f32_e32 v166, v174, v163
	v_sub_f32_e32 v163, v131, v191
	v_max3_f32 v162, v160, s0, v161
	v_add_f32_e32 v167, v175, v163
	v_max3_f32 v162, v162, v164, v165
	v_max3_f32 v170, v162, v166, v167
	v_sub_f32_e32 v162, v131, v192
	v_add_f32_e32 v162, v176, v162
	v_sub_f32_e32 v163, v131, v193
	v_add_f32_e32 v163, v177, v163
	v_sub_f32_e32 v171, v131, v178
	v_add_f32_e32 v100, v100, v171
	v_sub_f32_e32 v171, v131, v179
	v_add_f32_e32 v101, v101, v171
	v_sub_f32_e32 v171, v131, v180
	v_add_f32_e32 v102, v102, v171
	v_sub_f32_e32 v171, v131, v181
	v_add_f32_e32 v103, v103, v171
	v_sub_f32_e32 v171, v131, v182
	v_add_f32_e32 v96, v96, v171
	v_sub_f32_e32 v171, v131, v183
	v_add_f32_e32 v97, v97, v171
	v_sub_f32_e32 v171, v131, v184
	v_max3_f32 v170, v170, v162, v163
	v_add_f32_e32 v98, v98, v171
	v_max3_f32 v170, v170, v100, v101
	v_sub_f32_e32 v168, v131, v185
	v_max3_f32 v170, v170, v102, v103
	v_add_f32_e32 v99, v99, v168
	v_max3_f32 v170, v170, v96, v97
	s_branch .Lfox_join
